# fused RMSNorm epilogues: the four partner partial-sum loads issued together (one round trip instead of four)
# baseline (speedup 1.0000x reference)
.LBB0_94:
	s_waitcnt vmcnt(0) lgkmcnt(0)
	s_barrier
	ds_read_b32 v64, v65 offset:10240
	s_and_saveexec_b64 s[22:23], s[44:45]
	s_cbranch_execz .LBB0_96
	v_readlane_b32 s0, v249, 42
	v_lshlrev_b64 v[172:173], 5, v[226:227]
	v_readlane_b32 s1, v249, 43
	v_lshl_add_u32 v170, v170, 2, 0
	s_nop 0
	v_lshl_add_u64 v[172:173], s[0:1], 0, v[172:173]
	global_load_dwordx2 v[178:179], v[172:173], off sc1
	global_load_dwordx2 v[194:195], v[172:173], off offset:8 sc1
	global_load_dwordx2 v[196:197], v[172:173], off offset:16 sc1
	global_load_dwordx2 v[198:199], v[172:173], off offset:24 sc1
	s_mov_b32 s0, 0xf800000
	s_waitcnt vmcnt(0)
	v_add_f32_e32 v165, 0, v178
	v_add_f32_e32 v165, v165, v194
	v_add_f32_e32 v165, v165, v196
	v_add_f32_e32 v165, v165, v198
	v_fmamk_f32 v165, v165, 0x3a800000, v234
	v_cmp_gt_f32_e32 vcc, s0, v165
	v_mul_f32_e32 v171, 0x4f800000, v165
	s_nop 0
	v_cndmask_b32_e32 v165, v165, v171, vcc
	v_sqrt_f32_e32 v171, v165
	s_nop 0
	v_add_u32_e32 v172, -1, v171
	v_fma_f32 v173, -v172, v171, v165
	v_cmp_ge_f32_e64 s[0:1], 0, v173
	v_add_u32_e32 v173, 1, v171
	s_nop 0
	v_cndmask_b32_e64 v172, v171, v172, s[0:1]
	v_fma_f32 v171, -v173, v171, v165
	v_cmp_lt_f32_e64 s[0:1], 0, v171
	s_nop 1
	v_cndmask_b32_e64 v171, v172, v173, s[0:1]
	v_mul_f32_e32 v172, 0x37800000, v171
	v_cndmask_b32_e32 v171, v171, v172, vcc
	v_cmp_class_f32_e32 vcc, v165, v235
	s_nop 1
	v_cndmask_b32_e32 v165, v171, v165, vcc
	v_div_scale_f32 v171, s[0:1], v165, v165, 1.0
	v_rcp_f32_e32 v172, v171
	s_nop 0
	v_fma_f32 v173, -v171, v172, 1.0
	v_fmac_f32_e32 v172, v173, v172
	v_div_scale_f32 v173, vcc, 1.0, v165, 1.0
	v_mul_f32_e32 v178, v173, v172
	v_fma_f32 v179, -v171, v178, v173
	v_fmac_f32_e32 v178, v179, v172
	v_fma_f32 v171, -v171, v178, v173
	v_div_fmas_f32 v171, v171, v172, v178
	v_div_fixup_f32 v165, v171, v165, 1.0
	ds_write_b32 v170, v165 offset:8192

.LBB0_615:
	s_waitcnt vmcnt(0) lgkmcnt(0)
	s_barrier
	ds_read_b32 v64, v65 offset:10240
	s_and_saveexec_b64 s[28:29], s[44:45]
	s_cbranch_execz .LBB0_617
	v_add_u32_e32 v150, s52, v244
	v_ashrrev_i32_e32 v151, 31, v150
	v_readlane_b32 s0, v249, 42
	v_lshlrev_b64 v[150:151], 5, v[150:151]
	v_readlane_b32 s1, v249, 43
	s_nop 1
	v_lshl_add_u64 v[150:151], s[0:1], 0, v[150:151]
	global_load_dwordx2 v[152:153], v[150:151], off sc1
	global_load_dwordx2 v[174:175], v[150:151], off offset:8 sc1
	global_load_dwordx2 v[176:177], v[150:151], off offset:16 sc1
	global_load_dwordx2 v[186:187], v[150:151], off offset:24 sc1
	s_mov_b32 s0, 0xf800000
	s_waitcnt vmcnt(0)
	v_add_f32_e32 v149, 0, v152
	v_add_f32_e32 v149, v149, v174
	v_add_f32_e32 v149, v149, v176
	v_add_f32_e32 v149, v149, v186
	v_fmamk_f32 v149, v149, 0x3a800000, v234
	v_cmp_gt_f32_e32 vcc, s0, v149
	v_mul_f32_e32 v150, 0x4f800000, v149
	s_nop 0
	v_cndmask_b32_e32 v149, v149, v150, vcc
	v_sqrt_f32_e32 v150, v149
	s_nop 0
	v_add_u32_e32 v151, -1, v150
	v_fma_f32 v152, -v151, v150, v149
	v_cmp_ge_f32_e64 s[0:1], 0, v152
	v_add_u32_e32 v152, 1, v150
	s_nop 0
	v_cndmask_b32_e64 v151, v150, v151, s[0:1]
	v_fma_f32 v150, -v152, v150, v149
	v_cmp_lt_f32_e64 s[0:1], 0, v150
	s_nop 1
	v_cndmask_b32_e64 v150, v151, v152, s[0:1]
	v_mul_f32_e32 v151, 0x37800000, v150
	v_cndmask_b32_e32 v150, v150, v151, vcc
	v_cmp_class_f32_e32 vcc, v149, v235
	s_nop 1
	v_cndmask_b32_e32 v149, v150, v149, vcc
	v_div_scale_f32 v150, s[0:1], v149, v149, 1.0
	v_rcp_f32_e32 v151, v150
	s_nop 0
	v_fma_f32 v152, -v150, v151, 1.0
	v_fmac_f32_e32 v151, v152, v151
	v_div_scale_f32 v152, vcc, 1.0, v149, 1.0
	v_mul_f32_e32 v153, v152, v151
	v_fma_f32 v154, -v150, v153, v152
	v_fmac_f32_e32 v153, v154, v151
	v_fma_f32 v150, -v150, v153, v152
	v_div_fmas_f32 v150, v150, v151, v153
	v_div_fixup_f32 v149, v150, v149, 1.0
	v_lshl_add_u32 v150, v244, 2, 0
	ds_write_b32 v150, v149 offset:8192
